# v010_nbfast
# baseline (speedup 1.0000x reference)
; __device__ __forceinline__ void convert_item(const float* __restrict__ src, int Ksz, int Nsz, u16* __restrict__ dst, int kb, int nb,
;                                              int mode, const int tid) {
;   const int n = nb * NTHR + tid;
;   if (n < Nsz) {
;     const float* sp = src + (size_t)(kb * 64) * Nsz + n;
;     float v[64];
; #pragma unroll
;     for (int j = 0; j < 64; ++j) v[j] = sp[(size_t)j * Nsz];
;     int nd = n;
;     if (mode == 1) {
;       int isg = n >= 1024, c = n & 1023;
;       nd = (c >> 7) * 256 + isg * 128 + (c & 127);
;     }
; __device__ __forceinline__ void cv_in(const Params& p, int layer, int r, const int tid) {
;   int nb = r / (DM / 64), kb = r % (DM / 64);
;   convert_item(p.w_in + (size_t)layer * DM * DIN, DM, DIN, (u16*)(p.ws + WS_WIN + layer * SZ_WIN), kb, nb, 0, tid);
; }
; __device__ __forceinline__ void cv_out(const Params& p, int layer, int r, const int tid) {
;   int nb = r / 64, kb = r % 64;
;   convert_item(p.w_out + (size_t)layer * DM * DM, DM, DM, (u16*)(p.ws + WS_WOUT + layer * SZ_WOUT), kb, nb, 0, tid);
; }
; __device__ __forceinline__ void cv_glu(const Params& p, int layer, int r, const int tid) {
;   int nb = r / 16, kb = r % 16;
;   convert_item(p.w_glu + (size_t)layer * 1024 * 2048, 1024, 2048, (u16*)(p.ws + WS_WGLU + layer * SZ_WGLU), kb, nb, 1, tid);
; }
; __device__ __forceinline__ void cv_pool(const Params& p, int layer, int r, const int tid) {
;   int g = r / 4, kb = r % 4;
;   convert_item(p.w_pool + ((size_t)layer * 4 + g) * 65536, 256, 256, (u16*)(p.ws + WS_WPOOL + layer * SZ_WPOOL) + (size_t)g * 65536, kb,
;                0, 0, tid);
; }
; __device__ __forceinline__ void cv_item_B(const Params& p, int r, const int tid) {
;   if (r < CV_OUT) { cv_out(p, 0, r, tid); return; }
;   r -= CV_OUT;
;   if (r < CV_GLU) { cv_glu(p, 0, r, tid); return; }
;   r -= CV_GLU;
;   if (r < CV_IN) { cv_in(p, 1, r, tid); return; }
;   r -= CV_IN;
;   if (r < CV_OUT) { cv_out(p, 1, r, tid); return; }
;   r -= CV_OUT;
;   if (r < CV_GLU) { cv_glu(p, 1, r, tid); return; }
;   r -= CV_GLU;
;   cv_pool(p, 1, r, tid);
; }
.Lrot_done:
	s_cmpk_gt_i32 s64, 0x7f
	s_cbranch_scc0 .LBB0_197
	s_cmpk_gt_u32 s64, 0x17f
	s_cbranch_scc0 .LBB0_124
	s_cmpk_gt_u32 s64, 0x37f
	s_cbranch_scc0 .LBB0_115
	s_load_dwordx2 s[12:13], s[88:89], 0x80
	s_load_dwordx2 s[14:15], s[88:89], 0x68
	s_load_dwordx4 s[16:19], s[88:89], 0x10
	s_load_dwordx2 s[20:21], s[88:89], 0x98
	s_sub_u32 s6, s64, 0x380
	s_mov_b32 s27, 0
	s_waitcnt lgkmcnt(0)
	s_cmp_lt_u32 s6, 0x80
	s_cbranch_scc1 .Lcvm_wout0
	s_cmp_lt_u32 s6, 0x90
	s_cbranch_scc1 .Lcvm_glu0
	s_cmp_lt_u32 s6, 0x210
	s_cbranch_scc1 .Lcvm_win1
	s_cmp_lt_u32 s6, 0x290
	s_cbranch_scc1 .Lcvm_wout1
	s_cmp_lt_u32 s6, 0x2a0
	s_cbranch_scc1 .Lcvm_glu1
	s_sub_u32 s6, s6, 0x2a0
	s_lshl_b32 s28, s6, 18
	s_add_u32 s8, s18, s28
	s_addc_u32 s9, s19, 0
	s_add_u32 s8, s8, 0x100000
	s_addc_u32 s9, s9, 0
	s_lshl_b32 s28, s6, 17
	s_add_u32 s22, s20, s28
	s_addc_u32 s23, s21, 0
	s_add_u32 s22, s22, 0x10880000
	s_addc_u32 s23, s23, 0
	s_movk_i32 s24, 0x100
	s_movk_i32 s25, 0x100
	s_mov_b32 s26, 0
	s_mov_b32 s28, 0
	s_mov_b32 s29, 0
	s_branch .Lcvm_common
.Lcvm_wout0:
	s_and_b32 s28, s6, 7
	s_lshr_b32 s29, s6, 3
	s_mov_b64 s[8:9], s[12:13]
	s_add_u32 s22, s20, 0xc000000
	s_addc_u32 s23, s21, 0
	s_movk_i32 s24, 0x1000
	s_movk_i32 s25, 0x1000
	s_mov_b32 s26, 4
	s_branch .Lcvm_common
.Lcvm_glu0:
	s_sub_u32 s6, s6, 0x80
	s_and_b32 s28, s6, 3
	s_lshr_b32 s29, s6, 2
	s_mov_b64 s[8:9], s[14:15]
	s_add_u32 s22, s20, 0x10000000
	s_addc_u32 s23, s21, 0
	s_movk_i32 s24, 0x800
	s_movk_i32 s25, 0x400
	s_mov_b32 s26, 2
	s_mov_b32 s27, 1
	s_branch .Lcvm_common
.Lcvm_win1:
	s_sub_u32 s6, s6, 0x90
	s_mul_i32 s29, s6, 0xab
	s_lshr_b32 s29, s29, 12
	s_mul_i32 s28, s29, 24
	s_sub_u32 s28, s6, s28
	s_add_u32 s8, s16, 0xc000000
	s_addc_u32 s9, s17, 0
	s_add_u32 s22, s20, 0x6000000
	s_addc_u32 s23, s21, 0
	s_movk_i32 s24, 0x3000
	s_movk_i32 s25, 0x1000
	s_mov_b32 s26, 4
	s_branch .Lcvm_common
.Lcvm_wout1:
	s_sub_u32 s6, s6, 0x210
	s_and_b32 s28, s6, 7
	s_lshr_b32 s29, s6, 3
	s_add_u32 s8, s12, 0x4000000
	s_addc_u32 s9, s13, 0
	s_add_u32 s22, s20, 0xe000000
	s_addc_u32 s23, s21, 0
	s_movk_i32 s24, 0x1000
	s_movk_i32 s25, 0x1000
	s_mov_b32 s26, 4
	s_branch .Lcvm_common
.Lcvm_glu1:
	s_sub_u32 s6, s6, 0x290
	s_and_b32 s28, s6, 3
	s_lshr_b32 s29, s6, 2
	s_add_u32 s8, s14, 0x800000
	s_addc_u32 s9, s15, 0
	s_add_u32 s22, s20, 0x10400000
	s_addc_u32 s23, s21, 0
	s_movk_i32 s24, 0x800
	s_movk_i32 s25, 0x400
	s_mov_b32 s26, 2
	s_mov_b32 s27, 1
.Lcvm_common:
	s_lshl_b32 s29, s29, 8
	s_mul_i32 s30, s29, s24
	s_lshl_b32 s31, s28, 9
	s_add_u32 s30, s30, s31
	s_lshl_b32 s30, s30, 2
	s_add_u32 s8, s8, s30
	s_addc_u32 s9, s9, 0
	s_lshl_b32 s10, s24, 2
	v_add_u32_e32 v84, s31, v164
	v_cmp_gt_u32_e32 vcc, s24, v84
	s_and_b64 exec, exec, vcc
	s_cbranch_execz .Lcvm_done
	s_cmp_eq_u32 s27, 0
	s_cbranch_scc1 .Lcvm_nd
	v_and_b32_e32 v85, 0x3ff, v84
	v_lshrrev_b32_e32 v86, 7, v85
	v_lshlrev_b32_e32 v86, 8, v86
	v_and_b32_e32 v85, 0x7f, v85
	v_lshrrev_b32_e32 v87, 3, v84
	v_and_b32_e32 v87, 0x80, v87
	v_or3_b32 v84, v86, v85, v87
